# mLSTM chunk loop, both unrolled copies: DPP gate scan, DPP 8-lane butterfly sum, hoisted fragment reads with counted waits
# speedup vs baseline: 1.0102x; 1.0020x over previous
.LBB0_676:
	ds_read_b128 v[0:3], v131
	ds_read_b128 v[4:7], v131 offset:16
	ds_read_b128 v[8:11], v132
	ds_read_b128 v[12:15], v132 offset:16
	ds_read_b128 v[56:59], v132 offset:32
	ds_read_b128 v[60:63], v132 offset:48
	s_waitcnt lgkmcnt(5)
	v_lshlrev_b32_e32 v64, 16, v0
	v_and_b32_e32 v0, 0xffff0000, v0
	s_waitcnt lgkmcnt(3)
	v_mul_f32_e32 v0, v9, v0
	v_fmac_f32_e32 v0, v8, v64
	v_lshlrev_b32_e32 v8, 16, v1
	v_fmac_f32_e32 v0, v10, v8
	v_and_b32_e32 v1, 0xffff0000, v1
	v_fmac_f32_e32 v0, v11, v1
	v_lshlrev_b32_e32 v1, 16, v2
	s_waitcnt lgkmcnt(2)
	v_fmac_f32_e32 v0, v12, v1
	v_and_b32_e32 v1, 0xffff0000, v2
	v_fmac_f32_e32 v0, v13, v1
	v_lshlrev_b32_e32 v1, 16, v3
	v_fmac_f32_e32 v0, v14, v1
	v_and_b32_e32 v1, 0xffff0000, v3
	v_and_b32_e32 v2, 0xffff0000, v4
	v_fmac_f32_e32 v0, v15, v1
	v_lshlrev_b32_e32 v1, 16, v4
	s_waitcnt lgkmcnt(1)
	v_mul_f32_e32 v2, v57, v2
	v_fmac_f32_e32 v2, v56, v1
	v_lshlrev_b32_e32 v1, 16, v5
	v_fmac_f32_e32 v2, v58, v1
	v_and_b32_e32 v1, 0xffff0000, v5
	v_fmac_f32_e32 v2, v59, v1
	v_lshlrev_b32_e32 v1, 16, v6
	s_waitcnt lgkmcnt(0)
	v_fmac_f32_e32 v2, v60, v1
	v_and_b32_e32 v1, 0xffff0000, v6
	v_fmac_f32_e32 v2, v61, v1
	v_lshlrev_b32_e32 v1, 16, v7
	v_fmac_f32_e32 v2, v62, v1
	v_and_b32_e32 v1, 0xffff0000, v7
	v_add_f32_e32 v0, 0, v0
	v_fmac_f32_e32 v2, v63, v1
	v_add_f32_e32 v0, v0, v2
	s_nop 1
	v_add_f32_dpp v0, v0, v0 quad_perm:[1,0,3,2] row_mask:0xf bank_mask:0xf
	s_nop 1
	v_add_f32_dpp v0, v0, v0 quad_perm:[2,3,0,1] row_mask:0xf bank_mask:0xf
	s_nop 1
	v_mov_b32_dpp v1, v0 row_half_mirror row_mask:0xf bank_mask:0xf
	s_and_saveexec_b64 s[4:5], s[8:9]
	s_cbranch_execz .LBB0_678
	s_waitcnt lgkmcnt(0)
	v_add_f32_e32 v0, v0, v1
	ds_write_b32 v138, v0

.LBB0_699:
	s_waitcnt lgkmcnt(0)
	s_barrier
	s_and_b64 s[70:71], s[74:75], s[96:97]
	s_andn2_b64 vcc, exec, s[70:71]
	s_cbranch_vccnz .LBB0_703
	ds_read_b64 v[2:3], v156 offset:512
	v_max_f32_e32 v4, v172, v172
	s_waitcnt lgkmcnt(0)
	v_max_f32_e32 v1, v3, v3
	s_nop 1
	v_max_f32_dpp v1, v1, v1 row_shr:1 row_mask:0xf bank_mask:0xf
	s_nop 1
	v_max_f32_dpp v1, v1, v1 row_shr:2 row_mask:0xf bank_mask:0xf
	s_nop 1
	v_max_f32_dpp v1, v1, v1 row_shr:4 row_mask:0xf bank_mask:0xf
	s_nop 1
	v_max_f32_dpp v1, v1, v1 row_shr:8 row_mask:0xf bank_mask:0xf
	s_nop 1
	v_max_f32_dpp v1, v1, v1 row_bcast:15 row_mask:0xa bank_mask:0xf
	s_nop 1
	v_max_f32_dpp v1, v1, v1 row_bcast:31 row_mask:0xc bank_mask:0xf
	s_nop 1
	ds_bpermute_b32 v3, v130, v1
	ds_bpermute_b32 v0, v130, v2
	v_max_f32_e32 v1, v1, v1
	v_max_f32_e32 v1, v4, v1
	v_add_f32_e32 v1, v2, v1
	s_waitcnt lgkmcnt(1)
	v_max_f32_e32 v3, v3, v3
	v_sub_f32_e32 v2, v2, v1
	v_max_f32_e32 v3, v4, v3
	s_waitcnt lgkmcnt(0)
	v_add_f32_e32 v171, v3, v0
	v_mul_f32_e32 v3, 0x3fb8aa3b, v2
	v_add_f32_e32 v2, v172, v2
	v_mul_f32_e32 v2, 0x3fb8aa3b, v2
	v_mul_f32_e32 v1, 0xbfb8aa3b, v1
	v_exp_f32_e32 v3, v3
	v_exp_f32_e32 v2, v2
	v_exp_f32_e32 v1, v1
	ds_write2st64_b32 v153, v3, v2 offset1:1
	ds_write_b32 v153, v1 offset:512
	s_and_saveexec_b64 s[70:71], s[10:11]
	s_cbranch_execz .LBB0_702
	v_sub_f32_e32 v1, v0, v171
	v_add_f32_e32 v0, v172, v0
	v_sub_f32_e32 v0, v0, v171
	v_mul_f32_e32 v1, 0x3fb8aa3b, v1
	v_mul_f32_e32 v0, 0x3fb8aa3b, v0
	v_exp_f32_e32 v1, v1
	v_exp_f32_e32 v0, v0
	v_mov_b32_e32 v2, s78
	ds_write_b64 v2, v[0:1]

.LBB0_704:
	ds_read_b128 v[0:3], v131
	ds_read_b128 v[4:7], v131 offset:16
	ds_read_b128 v[8:11], v132
	ds_read_b128 v[12:15], v132 offset:16
	ds_read_b128 v[56:59], v132 offset:32
	ds_read_b128 v[60:63], v132 offset:48
	s_waitcnt lgkmcnt(5)
	v_lshlrev_b32_e32 v64, 16, v0
	v_and_b32_e32 v0, 0xffff0000, v0
	s_waitcnt lgkmcnt(3)
	v_mul_f32_e32 v0, v9, v0
	v_fmac_f32_e32 v0, v8, v64
	v_lshlrev_b32_e32 v8, 16, v1
	v_fmac_f32_e32 v0, v10, v8
	v_and_b32_e32 v1, 0xffff0000, v1
	v_fmac_f32_e32 v0, v11, v1
	v_lshlrev_b32_e32 v1, 16, v2
	s_waitcnt lgkmcnt(2)
	v_fmac_f32_e32 v0, v12, v1
	v_and_b32_e32 v1, 0xffff0000, v2
	v_fmac_f32_e32 v0, v13, v1
	v_lshlrev_b32_e32 v1, 16, v3
	v_fmac_f32_e32 v0, v14, v1
	v_and_b32_e32 v1, 0xffff0000, v3
	v_and_b32_e32 v2, 0xffff0000, v4
	v_fmac_f32_e32 v0, v15, v1
	v_lshlrev_b32_e32 v1, 16, v4
	s_waitcnt lgkmcnt(1)
	v_mul_f32_e32 v2, v57, v2
	v_fmac_f32_e32 v2, v56, v1
	v_lshlrev_b32_e32 v1, 16, v5
	v_fmac_f32_e32 v2, v58, v1
	v_and_b32_e32 v1, 0xffff0000, v5
	v_fmac_f32_e32 v2, v59, v1
	v_lshlrev_b32_e32 v1, 16, v6
	s_waitcnt lgkmcnt(0)
	v_fmac_f32_e32 v2, v60, v1
	v_and_b32_e32 v1, 0xffff0000, v6
	v_fmac_f32_e32 v2, v61, v1
	v_lshlrev_b32_e32 v1, 16, v7
	v_fmac_f32_e32 v2, v62, v1
	v_and_b32_e32 v1, 0xffff0000, v7
	v_add_f32_e32 v0, 0, v0
	v_fmac_f32_e32 v2, v63, v1
	v_add_f32_e32 v0, v0, v2
	s_nop 1
	v_add_f32_dpp v0, v0, v0 quad_perm:[1,0,3,2] row_mask:0xf bank_mask:0xf
	s_nop 1
	v_add_f32_dpp v0, v0, v0 quad_perm:[2,3,0,1] row_mask:0xf bank_mask:0xf
	s_nop 1
	v_mov_b32_dpp v1, v0 row_half_mirror row_mask:0xf bank_mask:0xf
	s_and_saveexec_b64 s[70:71], s[8:9]
	s_cbranch_execz .LBB0_706
	s_waitcnt lgkmcnt(0)
	v_add_f32_e32 v0, v0, v1
	ds_write_b32 v138, v0
.LBB0_706:
	s_or_b64 exec, exec, s[70:71]
	ds_read_b128 v[84:87], v88
	ds_read_b128 v[80:83], v88 offset:32
	ds_read_b128 v[76:79], v88 offset:64
	ds_read_b128 v[72:75], v88 offset:96
	ds_read_b128 v[68:71], v88 offset:128
	ds_read_b128 v[64:67], v88 offset:160
	ds_read_b128 v[60:63], v88 offset:192
	ds_read_b128 v[56:59], v88 offset:224
	s_and_b64 vcc, exec, s[56:57]
	s_mov_b64 s[70:71], -1
	s_cbranch_vccnz .LBB0_708
	s_waitcnt lgkmcnt(8)
	ds_read_b128 v[0:3], v157 offset:51200
	ds_read_b128 v[176:179], v157 offset:51232
	ds_read_b128 v[180:183], v157 offset:51264
	ds_read_b128 v[184:187], v157 offset:51296
	ds_read_b128 v[188:191], v157 offset:51328
	ds_read_b128 v[192:195], v157 offset:51360
	ds_read_b128 v[196:199], v157 offset:51392
	s_mov_b64 s[70:71], 0
	s_waitcnt lgkmcnt(6)
	v_mfma_f32_32x32x16_bf16 v[0:15], v[0:3], v[84:87], 0
	ds_read_b128 v[200:203], v157 offset:51424
	ds_read_b32 v172, v154 offset:256
	s_waitcnt lgkmcnt(7)
	v_mfma_f32_32x32x16_bf16 v[0:15], v[176:179], v[80:83], v[0:15]
	s_waitcnt lgkmcnt(6)
	v_mfma_f32_32x32x16_bf16 v[0:15], v[180:183], v[76:79], v[0:15]
	s_waitcnt lgkmcnt(5)
	v_mfma_f32_32x32x16_bf16 v[0:15], v[184:187], v[72:75], v[0:15]
	s_waitcnt lgkmcnt(4)
	v_mfma_f32_32x32x16_bf16 v[0:15], v[188:191], v[68:71], v[0:15]
	s_waitcnt lgkmcnt(3)
	v_mfma_f32_32x32x16_bf16 v[0:15], v[192:195], v[64:67], v[0:15]
	s_waitcnt lgkmcnt(2)
	v_mfma_f32_32x32x16_bf16 v[0:15], v[196:199], v[60:63], v[0:15]
	s_waitcnt lgkmcnt(1)
	v_mfma_f32_32x32x16_bf16 v[0:15], v[200:203], v[56:59], v[0:15]
	s_waitcnt lgkmcnt(0)
	s_nop 10
	v_pk_mul_f32 v[14:15], v[172:173], v[14:15] op_sel_hi:[0,1]
	v_pk_mul_f32 v[12:13], v[172:173], v[12:13] op_sel_hi:[0,1]
	v_pk_mul_f32 v[10:11], v[172:173], v[10:11] op_sel_hi:[0,1]
	v_pk_mul_f32 v[8:9], v[172:173], v[8:9] op_sel_hi:[0,1]
	v_pk_mul_f32 v[6:7], v[172:173], v[6:7] op_sel_hi:[0,1]
	v_pk_mul_f32 v[4:5], v[172:173], v[4:5] op_sel_hi:[0,1]
	v_pk_mul_f32 v[2:3], v[172:173], v[2:3] op_sel_hi:[0,1]
	v_pk_mul_f32 v[0:1], v[172:173], v[0:1] op_sel_hi:[0,1]
.LBB0_708:
	s_andn2_b64 vcc, exec, s[70:71]
	s_cbranch_vccnz .LBB0_712
	s_waitcnt lgkmcnt(8)
	ds_read_b128 v[0:3], v158 offset:17408
	ds_read_b128 v[180:183], v159 offset:17408
	ds_read_b128 v[184:187], v160 offset:17408
	ds_read_b128 v[188:191], v161 offset:17408
	ds_read_b128 v[192:195], v162 offset:17408
	ds_read_b128 v[196:199], v163 offset:17408
	ds_read_b128 v[200:203], v164 offset:17408
	s_waitcnt lgkmcnt(6)
	v_mfma_f32_32x32x16_bf16 v[0:15], v[0:3], v[84:87], 0
	ds_read_b128 v[204:207], v165 offset:17408
	ds_read_b32 v208, v154
	s_waitcnt lgkmcnt(7)
	v_mfma_f32_32x32x16_bf16 v[0:15], v[180:183], v[80:83], v[0:15]
	s_waitcnt lgkmcnt(6)
	v_mfma_f32_32x32x16_bf16 v[0:15], v[184:187], v[76:79], v[0:15]
	s_waitcnt lgkmcnt(5)
	v_mfma_f32_32x32x16_bf16 v[0:15], v[188:191], v[72:75], v[0:15]
	s_waitcnt lgkmcnt(4)
	v_mfma_f32_32x32x16_bf16 v[0:15], v[192:195], v[68:71], v[0:15]
	s_waitcnt lgkmcnt(3)
	v_mfma_f32_32x32x16_bf16 v[0:15], v[196:199], v[64:67], v[0:15]
	s_waitcnt lgkmcnt(2)
	v_mfma_f32_32x32x16_bf16 v[0:15], v[200:203], v[60:63], v[0:15]
	s_waitcnt lgkmcnt(1)
	v_mfma_f32_32x32x16_bf16 v[0:15], v[204:207], v[56:59], v[0:15]
	s_waitcnt lgkmcnt(0)
	s_nop 9
	v_mov_b32_e32 v58, v208
	v_mul_f32_e32 v56, v58, v0
	v_cndmask_b32_e64 v56, v56, 0, s[22:23]
	v_mul_f32_e32 v59, v58, v1
	v_add_f32_e32 v57, 0, v56
	v_cndmask_b32_e64 v59, 0, v59, s[24:25]
	v_mul_f32_e32 v60, v58, v2
	v_add_f32_e32 v57, v59, v57
	v_cndmask_b32_e64 v60, v60, 0, s[26:27]
	v_mul_f32_e32 v61, v58, v3
	v_add_f32_e32 v57, v60, v57
	v_cndmask_b32_e64 v61, v61, 0, s[28:29]
	v_cvt_pk_bf16_f32 v56, v56, v59
	v_add_f32_e32 v62, v61, v57
	v_cvt_pk_bf16_f32 v57, v60, v61
	ds_write_b64 v166, v[56:57] offset:41984
	v_mul_f32_e32 v56, v58, v4
	v_cndmask_b32_e64 v56, v56, 0, s[30:31]
	v_mul_f32_e32 v59, v58, v5
	v_add_f32_e32 v57, v56, v62
	v_cndmask_b32_e64 v59, v59, 0, s[34:35]
	v_mul_f32_e32 v60, v58, v6
	v_add_f32_e32 v57, v59, v57
	v_cndmask_b32_e64 v60, v60, 0, s[36:37]
	v_mul_f32_e32 v61, v58, v7
	v_add_f32_e32 v57, v60, v57
	v_cndmask_b32_e64 v61, v61, 0, s[38:39]
	v_cvt_pk_bf16_f32 v56, v56, v59
	v_add_f32_e32 v62, v61, v57
	v_cvt_pk_bf16_f32 v57, v60, v61
	ds_write_b64 v166, v[56:57] offset:42000
	v_mul_f32_e32 v56, v58, v8
	v_cndmask_b32_e64 v56, v56, 0, s[40:41]
	v_mul_f32_e32 v59, v58, v9
	v_add_f32_e32 v57, v56, v62
	v_cndmask_b32_e64 v59, v59, 0, s[42:43]
	v_mul_f32_e32 v60, v58, v10
	v_add_f32_e32 v57, v59, v57
	v_cndmask_b32_e64 v60, v60, 0, s[44:45]
	v_mul_f32_e32 v61, v58, v11
	v_add_f32_e32 v57, v60, v57
	v_cndmask_b32_e64 v61, v61, 0, s[46:47]
	v_cvt_pk_bf16_f32 v56, v56, v59
	v_add_f32_e32 v62, v61, v57
	v_cvt_pk_bf16_f32 v57, v60, v61
	ds_write_b64 v166, v[56:57] offset:42016
	v_mul_f32_e32 v56, v58, v12
	v_cndmask_b32_e64 v57, v56, 0, s[48:49]
	v_mul_f32_e32 v59, v58, v13
	v_add_f32_e32 v56, v57, v62
	v_cndmask_b32_e64 v59, v59, 0, s[50:51]
	v_mul_f32_e32 v60, v58, v14
	v_add_f32_e32 v56, v59, v56
	v_cndmask_b32_e64 v60, v60, 0, s[52:53]
	v_mul_f32_e32 v58, v58, v15
	v_add_f32_e32 v56, v60, v56
	v_cndmask_b32_e64 v61, v58, 0, s[54:55]
	v_add_f32_e32 v56, v61, v56
	v_cvt_pk_bf16_f32 v58, v57, v59
	ds_bpermute_b32 v57, v140, v56
	v_cvt_pk_bf16_f32 v59, v60, v61
	ds_write_b64 v166, v[58:59] offset:42032
	s_and_saveexec_b64 s[70:71], s[20:21]
	s_cbranch_execz .LBB0_711
	s_waitcnt lgkmcnt(1)
	v_add_f32_e32 v56, v56, v57
	v_add_u32_e32 v57, s58, v136
	ds_write_b32 v57, v56

.LBB0_712:
	s_waitcnt lgkmcnt(0)
	s_barrier
	s_and_b64 vcc, exec, s[56:57]
	s_cbranch_vccnz .LBB0_714
	s_waitcnt lgkmcnt(0)
	ds_read_b64_tr_b16 v[56:57], v174 offset:33792
	ds_read_b64_tr_b16 v[58:59], v174 offset:34048
	ds_read_b128 v[60:63], v167 offset:41984
	ds_read_b128 v[64:67], v167 offset:42016
	ds_read_b64_tr_b16 v[180:181], v174 offset:35840
	ds_read_b64_tr_b16 v[182:183], v174 offset:36096
	ds_read_b64_tr_b16 v[184:185], v174 offset:37888
	ds_read_b64_tr_b16 v[186:187], v174 offset:38144
	ds_read_b128 v[188:191], v167 offset:42048
	ds_read_b64_tr_b16 v[192:193], v174 offset:39936
	ds_read_b64_tr_b16 v[194:195], v174 offset:40192
	ds_read_b128 v[196:199], v167 offset:42080
	ds_read_b32 v204, v155
	ds_read_b32 v205, v143
	ds_read_b32 v206, v136
	s_waitcnt lgkmcnt(12)
	v_mfma_f32_32x32x16_bf16 v[0:15], v[56:59], v[60:63], v[0:15]
	s_waitcnt lgkmcnt(9)
	v_mfma_f32_32x32x16_bf16 v[0:15], v[180:183], v[64:67], v[0:15]
	ds_read_b32 v207, v144
	ds_read_b32 v208, v154 offset:512
	s_waitcnt lgkmcnt(8)
	v_mfma_f32_32x32x16_bf16 v[0:15], v[184:187], v[188:191], v[0:15]
	s_waitcnt lgkmcnt(5)
	v_mfma_f32_32x32x16_bf16 v[0:15], v[192:195], v[196:199], v[0:15]
	s_waitcnt lgkmcnt(2)
	v_mov_b32_e32 v58, v206
	v_fmac_f32_e32 v58, v204, v205
	s_waitcnt lgkmcnt(1)
	v_add_f32_e32 v56, v58, v207
	s_waitcnt lgkmcnt(0)
	v_max_f32_e32 v57, v208, v208
	v_max_f32_e64 v56, |v56|, v57
	v_div_scale_f32 v57, s[56:57], v56, v56, 1.0
	v_rcp_f32_e32 v58, v57
	s_mov_b32 s56, 0x1a010000
	v_fma_f32 v59, -v57, v58, 1.0
	v_fmac_f32_e32 v58, v59, v58
	v_div_scale_f32 v59, vcc, 1.0, v56, 1.0
	v_mul_f32_e32 v60, v59, v58
	v_fma_f32 v61, -v57, v60, v59
	v_fmac_f32_e32 v60, v61, v58
	v_fma_f32 v57, -v57, v60, v59
	v_div_fmas_f32 v57, v57, v58, v60
	v_div_fixup_f32 v56, v57, v56, 1.0
	v_mul_f32_e32 v0, v0, v56
	v_mul_f32_e32 v1, v1, v56
	v_cvt_pk_bf16_f32 v0, v0, v1
	v_mul_f32_e32 v1, v2, v56
	v_mul_f32_e32 v2, v3, v56
	v_cvt_pk_bf16_f32 v1, v1, v2
	v_add_co_u32_e32 v2, vcc, s56, v100
	s_nop 1
	v_addc_co_u32_e32 v3, vcc, 0, v101, vcc
	global_store_dwordx2 v[2:3], v[0:1], off
	v_mul_f32_e32 v0, v4, v56
	v_mul_f32_e32 v1, v5, v56
	v_cvt_pk_bf16_f32 v0, v0, v1
	v_mul_f32_e32 v1, v6, v56
	v_mul_f32_e32 v4, v7, v56
	v_cvt_pk_bf16_f32 v1, v1, v4
	global_store_dwordx2 v[2:3], v[0:1], off offset:16
	v_mul_f32_e32 v0, v8, v56
	v_mul_f32_e32 v1, v9, v56
	v_cvt_pk_bf16_f32 v0, v0, v1
	v_mul_f32_e32 v1, v10, v56
	v_mul_f32_e32 v4, v11, v56
	v_cvt_pk_bf16_f32 v1, v1, v4
	global_store_dwordx2 v[2:3], v[0:1], off offset:32
	v_mul_f32_e32 v0, v12, v56
	v_mul_f32_e32 v1, v13, v56
	v_cvt_pk_bf16_f32 v0, v0, v1
	v_mul_f32_e32 v1, v14, v56
	v_mul_f32_e32 v4, v15, v56
	v_cvt_pk_bf16_f32 v1, v1, v4
	global_store_dwordx2 v[2:3], v[0:1], off offset:48
